# v60 + non-temporal hint on the decode-attention KV-cache copy loads (read once)
# speedup vs baseline: 1.0129x; 1.0050x over previous
; #define LAS __attribute__((address_space(3)))
; DI void attn_decode_unit(LAS unsigned char* lds, const bf16_t* Z, const float* ck, const float* cv, bf16_t* MIX, const float* gq, const float* gk, const float* sinks, float* o_k, float* o_v, int b, int kh, int tid) {
;     ...
; #pragma unroll
;     for (int k = 0; k < 4; ++k) {
;         const int it = k * 512 + tid, w = it >> 4, c4 = (it & 15) * 4;
;         const size_t src = ((size_t)(b * 128 + w) * 2 + kh) * 64 + c4;
;         const f32x4 k4 = *(const f32x4*)(ck + src), v4 = *(const f32x4*)(cv + src);
;         *(LAS f32x4*)(Kc + w * 68 + c4) = k4; *(LAS f32x4*)(Vc + w * 64 + c4) = v4;
;         if (w >= 1) { const size_t dst = ((size_t)(b * 128 + w - 1) * 2 + kh) * 64 + c4; *(f32x4*)(o_k + dst) = k4; *(f32x4*)(o_v + dst) = v4; }
;     }
.LBB0_312:
	s_ashr_i32 s7, s13, 1
	s_lshl_b32 s6, s7, 7
	v_or_b32_e32 v0, s6, v41
	v_ashrrev_i32_e32 v1, 31, v0
	s_and_b32 s25, s13, 1
	v_lshlrev_b64 v[10:11], 7, v[0:1]
	s_lshl_b32 s20, s25, 6
	v_or_b32_e32 v12, v10, v40
	v_or_b32_e32 v10, s20, v12
	v_lshlrev_b64 v[4:5], 2, v[10:11]
	v_lshl_add_u64 v[0:1], s[48:49], 0, v[4:5]
	v_lshl_add_u64 v[4:5], s[50:51], 0, v[4:5]
	global_load_dwordx4 v[0:3], v[0:1], off nt
	s_nop 0
	global_load_dwordx4 v[4:7], v[4:5], off nt
	s_waitcnt vmcnt(0)
	ds_write_b128 v54, v[0:3]
	ds_write_b128 v55, v[4:7] offset:35088
	s_and_saveexec_b64 s[4:5], s[90:91]
	s_cbranch_execz .LBB0_314
	v_mov_b32_e32 v13, v11
	v_lshl_add_u64 v[10:11], v[12:13], 0, s[20:21]
	v_lshl_add_u64 v[10:11], v[10:11], 2, s[22:23]
	v_lshl_add_u64 v[12:13], s[14:15], 0, v[10:11]
	global_store_dwordx4 v[12:13], v[0:3], off
	s_nop 1
	v_lshl_add_u64 v[0:1], s[16:17], 0, v[10:11]
	global_store_dwordx4 v[0:1], v[4:7], off
.LBB0_314:
	s_or_b64 exec, exec, s[4:5]
	v_or_b32_e32 v0, s6, v42
	v_ashrrev_i32_e32 v1, 31, v0
	v_lshlrev_b64 v[0:1], 7, v[0:1]
	v_or_b32_e32 v0, v0, v40
	v_or_b32_e32 v2, s20, v0
	v_mov_b32_e32 v3, v1
	v_lshlrev_b64 v[6:7], 2, v[2:3]
	v_lshl_add_u64 v[2:3], s[48:49], 0, v[6:7]
	global_load_dwordx4 v[2:5], v[2:3], off nt
	v_lshl_add_u64 v[6:7], s[50:51], 0, v[6:7]
	global_load_dwordx4 v[10:13], v[6:7], off nt
	v_or_b32_e32 v6, s6, v43
	v_ashrrev_i32_e32 v7, 31, v6
	v_lshlrev_b64 v[6:7], 7, v[6:7]
	v_or_b32_e32 v6, v6, v40
	v_lshl_add_u64 v[0:1], v[0:1], 0, s[20:21]
	v_mov_b32_e32 v29, v7
	v_or_b32_e32 v28, s20, v6
	v_lshl_add_u64 v[0:1], v[0:1], 2, s[22:23]
	v_lshlrev_b64 v[28:29], 2, v[28:29]
	v_lshl_add_u64 v[30:31], s[14:15], 0, v[0:1]
	v_lshl_add_u64 v[0:1], s[16:17], 0, v[0:1]
	v_lshl_add_u64 v[32:33], s[48:49], 0, v[28:29]
	v_lshl_add_u64 v[34:35], s[50:51], 0, v[28:29]
	v_add_u32_e32 v36, s6, v44
	v_ashrrev_i32_e32 v37, 31, v36
	v_lshlrev_b64 v[68:69], 7, v[36:37]
	v_or_b32_e32 v68, v68, v40
	v_lshl_add_u64 v[6:7], v[6:7], 0, s[20:21]
	v_mov_b32_e32 v37, v69
	v_or_b32_e32 v36, s20, v68
	v_lshlrev_b64 v[36:37], 2, v[36:37]
	v_lshl_add_u64 v[64:65], s[48:49], 0, v[36:37]
	v_lshl_add_u64 v[66:67], s[50:51], 0, v[36:37]
	s_add_i32 s24, s7, 0x2000
	s_mul_i32 s4, s24, 0x2a00
	s_mul_hi_i32 s5, s24, 0x2a00
	s_add_u32 s4, s54, s4
	s_addc_u32 s5, s55, s5
	s_or_b32 s6, s6, 0x7f
	s_ashr_i32 s7, s6, 31
	v_mov_b32_e32 v72, s20
	s_lshl_b64 s[6:7], s[6:7], 7
	v_add_u32_e32 v8, v56, v57
	v_add_u32_e32 v25, v56, v58
	v_add_u32_e32 v63, v56, v59
	v_add_u32_e32 v70, v56, v60
	v_add_u32_e32 v71, v56, v61
	s_waitcnt vmcnt(1)
	global_store_dwordx4 v[30:31], v[2:5], off
	s_waitcnt vmcnt(1)
	global_store_dwordx4 v[0:1], v[10:13], off
	global_load_dwordx4 v[28:31], v[32:33], off nt
	s_nop 0
	global_load_dwordx4 v[32:35], v[34:35], off nt
	v_mov_b64_e32 v[0:1], s[22:23]
	v_lshl_add_u64 v[6:7], v[6:7], 2, v[0:1]
	v_lshl_add_u64 v[38:39], s[14:15], 0, v[6:7]
	v_lshl_add_u64 v[6:7], s[16:17], 0, v[6:7]
	s_waitcnt vmcnt(1)
	global_store_dwordx4 v[38:39], v[28:31], off
	s_waitcnt vmcnt(1)
	global_store_dwordx4 v[6:7], v[32:35], off
	global_load_dwordx4 v[36:39], v[64:65], off nt
	s_nop 0
	global_load_dwordx4 v[64:67], v[66:67], off nt
	v_lshl_add_u64 v[6:7], v[68:69], 0, s[20:21]
	v_lshl_add_u64 v[0:1], v[6:7], 2, v[0:1]
	v_lshl_add_u64 v[6:7], s[14:15], 0, v[0:1]
	v_lshl_add_u64 v[68:69], s[16:17], 0, v[0:1]
	v_or3_b32 v1, s7, 0, 0
	v_or3_b32 v0, s6, v72, v152
	ds_write_b128 v8, v[2:5]
	ds_write_b128 v25, v[10:13] offset:35088
	ds_write_b128 v54, v[28:31] offset:17408
	ds_write_b128 v63, v[32:35] offset:35088
	s_waitcnt vmcnt(1)
	ds_write_b128 v70, v[36:39]
	s_waitcnt vmcnt(0)
	ds_write_b128 v71, v[64:67] offset:35088
	global_store_dwordx4 v[6:7], v[36:39], off
	global_store_dwordx4 v[68:69], v[64:67], off
	s_and_saveexec_b64 s[6:7], s[0:1]
	s_cbranch_execz .LBB0_316
	v_or_b32_e32 v2, s20, v253
	v_lshlrev_b32_e32 v2, 1, v2
	global_load_ushort v2, v2, s[4:5] offset:2048
	s_nop 0
	global_load_dword v4, v[20:21], off
	s_waitcnt vmcnt(1)
	v_lshlrev_b32_e32 v5, 16, v2
	v_mul_f32_e32 v2, v5, v5
	ds_bpermute_b32 v2, v14, v2
	s_waitcnt lgkmcnt(0)
	v_fmac_f32_e32 v2, v5, v5
	ds_bpermute_b32 v3, v15, v2
	s_waitcnt lgkmcnt(0)
	v_add_f32_e32 v2, v2, v3
	ds_bpermute_b32 v3, v16, v2
	s_waitcnt lgkmcnt(0)
	v_add_f32_e32 v2, v2, v3
	ds_bpermute_b32 v3, v17, v2
	s_waitcnt lgkmcnt(0)
	v_add_f32_e32 v2, v2, v3
	ds_bpermute_b32 v3, v18, v2
	s_waitcnt lgkmcnt(0)
	v_add_f32_e32 v2, v2, v3
	ds_bpermute_b32 v3, v19, v2
	s_waitcnt lgkmcnt(0)
	v_add_f32_e32 v2, v2, v3
	v_fmamk_f32 v2, v2, 0x3c800000, v27
	v_mul_f32_e32 v3, 0x4b800000, v2
	v_cmp_gt_f32_e32 vcc, s12, v2
	s_nop 1
	v_cndmask_b32_e32 v2, v2, v3, vcc
	v_rsq_f32_e32 v6, v2
	v_lshl_add_u64 v[2:3], v[0:1], 2, s[14:15]
	v_mul_f32_e32 v7, 0x45800000, v6
	v_cndmask_b32_e32 v6, v6, v7, vcc
	v_mul_f32_e32 v5, v6, v5
	s_waitcnt vmcnt(0)
	v_mul_f32_e32 v4, v4, v5
	ds_write_b32 v45, v4 offset:34816
	global_store_dword v[2:3], v4, off

; #define LAS __attribute__((address_space(3)))
; DI void attn_decode_unit(LAS unsigned char* lds, const bf16_t* Z, const float* ck, const float* cv, bf16_t* MIX, const float* gq, const float* gk, const float* sinks, float* o_k, float* o_v, int b, int kh, int tid) {
;     ...
; #pragma unroll
;     for (int k = 0; k < 4; ++k) {
;         const int it = k * 512 + tid, w = it >> 4, c4 = (it & 15) * 4;
;         const size_t src = ((size_t)(b * 128 + w) * 2 + kh) * 64 + c4;
;         const f32x4 k4 = *(const f32x4*)(ck + src), v4 = *(const f32x4*)(cv + src);
;         *(LAS f32x4*)(Kc + w * 68 + c4) = k4; *(LAS f32x4*)(Vc + w * 64 + c4) = v4;
;         if (w >= 1) { const size_t dst = ((size_t)(b * 128 + w - 1) * 2 + kh) * 64 + c4; *(f32x4*)(o_k + dst) = k4; *(f32x4*)(o_v + dst) = v4; }
;     }
.LBB0_336:
	s_ashr_i32 s5, s13, 1
	s_lshl_b32 s4, s5, 7
	v_or_b32_e32 v0, s4, v41
	v_ashrrev_i32_e32 v1, 31, v0
	s_and_b32 s21, s13, 1
	v_lshlrev_b64 v[12:13], 7, v[0:1]
	s_lshl_b32 s6, s21, 6
	v_or_b32_e32 v14, v12, v40
	v_or_b32_e32 v12, s6, v14
	v_lshlrev_b64 v[4:5], 2, v[12:13]
	v_lshl_add_u64 v[0:1], s[48:49], 0, v[4:5]
	v_lshl_add_u64 v[4:5], s[50:51], 0, v[4:5]
	global_load_dwordx4 v[0:3], v[0:1], off nt
	s_nop 0
	global_load_dwordx4 v[4:7], v[4:5], off nt
	s_waitcnt vmcnt(0)
	ds_write_b128 v54, v[0:3]
	ds_write_b128 v55, v[4:7] offset:35088
	s_and_saveexec_b64 s[2:3], s[90:91]
	s_cbranch_execz .LBB0_338
	v_mov_b32_e32 v15, v13
	v_lshl_add_u64 v[12:13], v[14:15], 0, s[6:7]
	v_lshl_add_u64 v[12:13], v[12:13], 2, s[18:19]
	v_lshl_add_u64 v[14:15], s[14:15], 0, v[12:13]
	global_store_dwordx4 v[14:15], v[0:3], off
	s_nop 1
	v_lshl_add_u64 v[0:1], s[16:17], 0, v[12:13]
	global_store_dwordx4 v[0:1], v[4:7], off
.LBB0_338:
	s_or_b64 exec, exec, s[2:3]
	v_or_b32_e32 v0, s4, v42
	v_ashrrev_i32_e32 v1, 31, v0
	v_lshlrev_b64 v[0:1], 7, v[0:1]
	v_or_b32_e32 v0, v0, v40
	v_or_b32_e32 v2, s6, v0
	v_mov_b32_e32 v3, v1
	v_lshlrev_b64 v[6:7], 2, v[2:3]
	v_lshl_add_u64 v[2:3], s[48:49], 0, v[6:7]
	global_load_dwordx4 v[2:5], v[2:3], off nt
	v_lshl_add_u64 v[6:7], s[50:51], 0, v[6:7]
	global_load_dwordx4 v[12:15], v[6:7], off nt
	v_or_b32_e32 v6, s4, v43
	v_ashrrev_i32_e32 v7, 31, v6
	v_lshlrev_b64 v[6:7], 7, v[6:7]
	v_or_b32_e32 v6, v6, v40
	v_lshl_add_u64 v[0:1], v[0:1], 0, s[6:7]
	v_mov_b32_e32 v37, v7
	v_or_b32_e32 v36, s6, v6
	v_lshl_add_u64 v[0:1], v[0:1], 2, v[8:9]
	v_lshlrev_b64 v[36:37], 2, v[36:37]
	v_lshl_add_u64 v[38:39], s[14:15], 0, v[0:1]
	v_lshl_add_u64 v[0:1], s[16:17], 0, v[0:1]
	v_lshl_add_u64 v[56:57], s[48:49], 0, v[36:37]
	v_lshl_add_u64 v[58:59], s[50:51], 0, v[36:37]
	v_lshl_add_u64 v[6:7], v[6:7], 0, s[6:7]
	v_lshl_add_u64 v[6:7], v[6:7], 2, v[8:9]
	v_lshl_add_u64 v[62:63], s[14:15], 0, v[6:7]
	v_lshl_add_u64 v[6:7], s[16:17], 0, v[6:7]
	s_add_i32 s20, s5, 0x2000
	s_mul_i32 s2, s20, 0x2a00
	s_mul_hi_i32 s3, s20, 0x2a00
	s_add_u32 s2, s54, s2
	s_addc_u32 s3, s55, s3
	v_mov_b32_e32 v10, s6
	s_waitcnt vmcnt(1)
	global_store_dwordx4 v[38:39], v[2:5], off
	s_waitcnt vmcnt(1)
	global_store_dwordx4 v[0:1], v[12:15], off
	global_load_dwordx4 v[36:39], v[56:57], off nt
	s_nop 0
	global_load_dwordx4 v[56:59], v[58:59], off nt
	v_add_u32_e32 v0, s4, v44
	v_ashrrev_i32_e32 v1, 31, v0
	v_lshlrev_b64 v[0:1], 7, v[0:1]
	v_or_b32_e32 v0, v0, v40
	v_mov_b32_e32 v61, v1
	v_or_b32_e32 v60, s6, v0
	v_lshlrev_b64 v[60:61], 2, v[60:61]
	v_lshl_add_u64 v[64:65], s[48:49], 0, v[60:61]
	v_lshl_add_u64 v[66:67], s[50:51], 0, v[60:61]
	s_or_b32 s4, s4, 0x7f
	v_lshl_add_u64 v[0:1], v[0:1], 0, s[6:7]
	s_ashr_i32 s5, s4, 31
	v_lshl_add_u64 v[0:1], v[0:1], 2, v[8:9]
	s_lshl_b64 s[4:5], s[4:5], 7
	v_lshl_add_u64 v[68:69], s[16:17], 0, v[0:1]
	s_waitcnt vmcnt(1)
	global_store_dwordx4 v[62:63], v[36:39], off
	s_waitcnt vmcnt(1)
	global_store_dwordx4 v[6:7], v[56:59], off
	global_load_dwordx4 v[60:63], v[64:65], off nt
	s_nop 0
	global_load_dwordx4 v[64:67], v[66:67], off nt
	v_lshl_add_u64 v[6:7], s[14:15], 0, v[0:1]
	v_or3_b32 v1, s5, 0, 0
	v_or3_b32 v0, s4, v10, v152
	ds_write_b128 v29, v[2:5]
	ds_write_b128 v30, v[12:15] offset:35088
	ds_write_b128 v54, v[36:39] offset:17408
	ds_write_b128 v31, v[56:59] offset:35088
	s_waitcnt vmcnt(1)
	ds_write_b128 v32, v[60:63]
	s_waitcnt vmcnt(0)
	ds_write_b128 v33, v[64:67] offset:35088
	global_store_dwordx4 v[6:7], v[60:63], off
	global_store_dwordx4 v[68:69], v[64:67], off
	s_and_saveexec_b64 s[4:5], s[0:1]
	s_cbranch_execz .LBB0_340
	v_or_b32_e32 v2, s6, v253
	v_lshlrev_b32_e32 v2, 1, v2
	global_load_ushort v2, v2, s[2:3] offset:2048
	s_nop 0
	global_load_dword v4, v[20:21], off
	s_waitcnt vmcnt(1)
	v_lshlrev_b32_e32 v5, 16, v2
	v_mul_f32_e32 v2, v5, v5
	ds_bpermute_b32 v2, v16, v2
	s_waitcnt lgkmcnt(0)
	v_fmac_f32_e32 v2, v5, v5
	ds_bpermute_b32 v3, v17, v2
	s_waitcnt lgkmcnt(0)
	v_add_f32_e32 v2, v2, v3
	ds_bpermute_b32 v3, v18, v2
	s_waitcnt lgkmcnt(0)
	v_add_f32_e32 v2, v2, v3
	ds_bpermute_b32 v3, v19, v2
	s_waitcnt lgkmcnt(0)
	v_add_f32_e32 v2, v2, v3
	ds_bpermute_b32 v3, v26, v2
	s_waitcnt lgkmcnt(0)
	v_add_f32_e32 v2, v2, v3
	ds_bpermute_b32 v3, v27, v2
	s_waitcnt lgkmcnt(0)
	v_add_f32_e32 v2, v2, v3
	v_fmamk_f32 v2, v2, 0x3c800000, v34
	v_mul_f32_e32 v3, 0x4b800000, v2
	v_cmp_gt_f32_e32 vcc, s12, v2
	s_nop 1
	v_cndmask_b32_e32 v2, v2, v3, vcc
	v_rsq_f32_e32 v6, v2
	v_lshl_add_u64 v[2:3], v[0:1], 2, s[14:15]
	v_mul_f32_e32 v7, 0x45800000, v6
	v_cndmask_b32_e32 v6, v6, v7, vcc
	v_mul_f32_e32 v5, v6, v5
	s_waitcnt vmcnt(0)
	v_mul_f32_e32 v4, v4, v5
	ds_write_b32 v45, v4 offset:34816
	global_store_dword v[2:3], v4, off
